# grid seams: invalidate issued while waiting (non-leaders after first poll, XCD leader with its writeback) instead of after release
# speedup vs baseline: 1.0197x; 1.0087x over previous
.LBB0_173:
	s_or_b64 exec, exec, s[8:9]
	v_cvt_f32_u32_e32 v4, v2
	s_waitcnt vmcnt(0)
	v_readfirstlane_b32 s3, v3
	v_sub_u32_e32 v3, 0, v2
	v_rcp_iflag_f32_e32 v4, v4
	v_add_u32_e32 v5, s3, v1
	v_mul_f32_e32 v4, 0x4f7ffffe, v4
	v_cvt_u32_f32_e32 v4, v4
	v_mul_lo_u32 v1, v3, v4
	v_mul_hi_u32 v1, v4, v1
	v_add_u32_e32 v1, v4, v1
	v_mul_hi_u32 v1, v5, v1
	v_mul_lo_u32 v3, v1, v2
	v_sub_u32_e32 v3, v5, v3
	v_add_u32_e32 v4, 1, v1
	v_cmp_ge_u32_e32 vcc, v3, v2
	s_nop 1
	v_cndmask_b32_e32 v1, v1, v4, vcc
	v_sub_u32_e32 v4, v3, v2
	v_cndmask_b32_e32 v3, v3, v4, vcc
	v_add_u32_e32 v4, 1, v1
	v_cmp_ge_u32_e32 vcc, v3, v2
	v_add_u32_e32 v3, 1, v5
	s_nop 0
	v_cndmask_b32_e32 v1, v1, v4, vcc
	v_mul_lo_u32 v4, v2, v1
	v_add_u32_e32 v2, v4, v2
	v_cmp_ne_u32_e32 vcc, v3, v2
	s_and_saveexec_b64 s[6:7], vcc
	s_xor_b64 s[6:7], exec, s[6:7]
	s_cbranch_execz .LBB0_187
	s_waitcnt lgkmcnt(0)
	v_mov_b32_e32 v0, 0x2000
	global_load_dword v0, v0, s[4:5] offset:1024 sc1
	buffer_inv sc1
	s_add_u32 s12, s4, 0x2400
	s_addc_u32 s13, s5, 0
	s_waitcnt vmcnt(1)
	v_cmp_eq_u32_e32 vcc, v0, v1
	s_and_saveexec_b64 s[8:9], vcc
	s_cbranch_execz .LBB0_186
	s_add_u32 s10, s42, 0x1200
	s_addc_u32 s11, s43, 0
	s_mov_b32 s3, 1
	s_mov_b64 s[14:15], 0
	v_mov_b32_e32 v0, 0
	s_branch .LBB0_177

.LBB0_186:
	s_or_b64 exec, exec, s[8:9]
	s_waitcnt vmcnt(0)
	s_waitcnt vmcnt(0)
.LBB0_187:
	s_andn2_saveexec_b64 s[6:7], s[6:7]
	s_cbranch_execz .LBB0_207
	s_mov_b64 s[6:7], exec
	buffer_wbl2 sc1
	buffer_inv sc1
	s_waitcnt lgkmcnt(0)
	s_waitcnt vmcnt(0)
	v_mbcnt_lo_u32_b32 v1, s6, 0
	v_mbcnt_hi_u32_b32 v1, s7, v1
	v_cmp_eq_u32_e32 vcc, 0, v1
	s_and_saveexec_b64 s[8:9], vcc
	s_cbranch_execz .LBB0_190
	s_bcnt1_i32_b64 s3, s[6:7]
	v_mov_b32_e32 v2, 0x4000
	v_mov_b32_e32 v3, s3
	global_atomic_add v2, v2, v3, s[42:43] offset:1024 sc0

.LBB0_204:
	s_or_b64 exec, exec, s[6:7]
	s_mov_b64 s[6:7], exec
	v_mbcnt_lo_u32_b32 v0, s6, 0
	v_mbcnt_hi_u32_b32 v0, s7, v0
	v_cmp_eq_u32_e32 vcc, 0, v0
	s_waitcnt vmcnt(0)
	s_and_saveexec_b64 s[8:9], vcc
	s_cbranch_execz .LBB0_206
	s_bcnt1_i32_b64 s3, s[6:7]
	v_mov_b32_e32 v0, 0x2000
	v_mov_b32_e32 v1, s3
	global_atomic_add v0, v1, s[4:5] offset:1024

.LBB0_365:
	s_or_b64 exec, exec, s[8:9]
	v_cvt_f32_u32_e32 v4, v2
	s_waitcnt vmcnt(0)
	v_readfirstlane_b32 s3, v3
	v_sub_u32_e32 v3, 0, v2
	v_rcp_iflag_f32_e32 v4, v4
	v_add_u32_e32 v5, s3, v1
	v_mul_f32_e32 v4, 0x4f7ffffe, v4
	v_cvt_u32_f32_e32 v4, v4
	v_mul_lo_u32 v1, v3, v4
	v_mul_hi_u32 v1, v4, v1
	v_add_u32_e32 v1, v4, v1
	v_mul_hi_u32 v1, v5, v1
	v_mul_lo_u32 v3, v1, v2
	v_sub_u32_e32 v3, v5, v3
	v_add_u32_e32 v4, 1, v1
	v_cmp_ge_u32_e32 vcc, v3, v2
	s_nop 1
	v_cndmask_b32_e32 v1, v1, v4, vcc
	v_sub_u32_e32 v4, v3, v2
	v_cndmask_b32_e32 v3, v3, v4, vcc
	v_add_u32_e32 v4, 1, v1
	v_cmp_ge_u32_e32 vcc, v3, v2
	v_add_u32_e32 v3, 1, v5
	s_nop 0
	v_cndmask_b32_e32 v1, v1, v4, vcc
	v_mul_lo_u32 v4, v2, v1
	v_add_u32_e32 v2, v4, v2
	v_cmp_ne_u32_e32 vcc, v3, v2
	s_and_saveexec_b64 s[6:7], vcc
	s_xor_b64 s[6:7], exec, s[6:7]
	s_cbranch_execz .LBB0_379
	s_waitcnt lgkmcnt(0)
	v_mov_b32_e32 v0, 0x2000
	global_load_dword v0, v0, s[4:5] offset:1024 sc1
	buffer_inv sc1
	s_add_u32 s10, s4, 0x2400
	s_addc_u32 s11, s5, 0
	s_waitcnt vmcnt(1)
	v_cmp_eq_u32_e32 vcc, v0, v1
	s_and_saveexec_b64 s[8:9], vcc
	s_cbranch_execz .LBB0_378
	s_mov_b32 s3, 1
	s_mov_b64 s[12:13], 0
	s_branch .LBB0_369

.LBB0_379:
	s_andn2_saveexec_b64 s[6:7], s[6:7]
	s_cbranch_execz .LBB0_399
	s_mov_b64 s[6:7], exec
	buffer_wbl2 sc1
	buffer_inv sc1
	s_waitcnt lgkmcnt(0)
	s_waitcnt vmcnt(0)
	v_mbcnt_lo_u32_b32 v1, s6, 0
	v_mbcnt_hi_u32_b32 v1, s7, v1
	v_cmp_eq_u32_e32 vcc, 0, v1
	s_and_saveexec_b64 s[8:9], vcc
	s_cbranch_execz .LBB0_382
	s_bcnt1_i32_b64 s3, s[6:7]
	v_readlane_b32 s6, v254, 9
	v_mov_b32_e32 v2, s3
	v_readlane_b32 s7, v254, 10
	s_nop 4
	global_atomic_add v2, v195, v2, s[6:7] sc0

.LBB0_396:
	s_or_b64 exec, exec, s[6:7]
	s_mov_b64 s[6:7], exec
	v_mbcnt_lo_u32_b32 v0, s6, 0
	v_mbcnt_hi_u32_b32 v0, s7, v0
	v_cmp_eq_u32_e32 vcc, 0, v0
	s_waitcnt vmcnt(0)
	s_and_saveexec_b64 s[8:9], vcc
	s_cbranch_execz .LBB0_398
	s_bcnt1_i32_b64 s3, s[6:7]
	v_mov_b32_e32 v0, s3
	v_mov_b32_e32 v1, 0x2000
	global_atomic_add v1, v0, s[4:5] offset:1024

.Lconv_rebal:
	s_cmpk_gt_i32 s3, 0xff
	s_cbranch_scc1 .LBB0_404
	s_and_b32 s11, s2, 0x78
	s_cmp_lg_u32 s11, 0
	s_cbranch_scc1 .LBB0_404
	s_lshr_b32 s11, s2, 7
	s_lshl_b32 s11, s11, 3
	s_and_b32 s10, s2, 7
	s_add_i32 s11, s11, s10
	s_addk_i32 s11, 0x100
	s_sub_i32 s10, s11, s3
	s_lshl_b32 s10, s10, 6
	v_add_u32_e32 v80, s10, v80
	s_mov_b32 s3, s11

.LBB0_628:
	s_or_b64 exec, exec, s[10:11]
	v_cvt_f32_u32_e32 v4, v2
	s_waitcnt vmcnt(0)
	v_readfirstlane_b32 s3, v3
	v_sub_u32_e32 v3, 0, v2
	v_rcp_iflag_f32_e32 v4, v4
	v_add_u32_e32 v5, s3, v1
	v_mul_f32_e32 v4, 0x4f7ffffe, v4
	v_cvt_u32_f32_e32 v4, v4
	v_mul_lo_u32 v1, v3, v4
	v_mul_hi_u32 v1, v4, v1
	v_add_u32_e32 v1, v4, v1
	v_mul_hi_u32 v1, v5, v1
	v_mul_lo_u32 v3, v1, v2
	v_sub_u32_e32 v3, v5, v3
	v_add_u32_e32 v4, 1, v1
	v_cmp_ge_u32_e32 vcc, v3, v2
	s_nop 1
	v_cndmask_b32_e32 v1, v1, v4, vcc
	v_sub_u32_e32 v4, v3, v2
	v_cndmask_b32_e32 v3, v3, v4, vcc
	v_add_u32_e32 v4, 1, v1
	v_cmp_ge_u32_e32 vcc, v3, v2
	v_add_u32_e32 v3, 1, v5
	s_nop 0
	v_cndmask_b32_e32 v1, v1, v4, vcc
	v_mul_lo_u32 v4, v2, v1
	v_add_u32_e32 v2, v4, v2
	v_cmp_ne_u32_e32 vcc, v3, v2
	s_and_saveexec_b64 s[6:7], vcc
	s_xor_b64 s[8:9], exec, s[6:7]
	s_cbranch_execz .LBB0_642
	s_waitcnt lgkmcnt(0)
	v_mov_b32_e32 v0, 0x2000
	global_load_dword v0, v0, s[4:5] offset:1024 sc1
	buffer_inv sc1
	s_add_u32 s12, s4, 0x2400
	s_addc_u32 s13, s5, 0
	s_waitcnt vmcnt(1)
	v_cmp_eq_u32_e32 vcc, v0, v1
	s_and_saveexec_b64 s[10:11], vcc
	s_cbranch_execz .LBB0_641
	s_mov_b32 s3, 1
	s_mov_b64 s[14:15], 0
	s_branch .LBB0_632

.LBB0_641:
	s_or_b64 exec, exec, s[10:11]
	s_waitcnt vmcnt(0)
	s_waitcnt vmcnt(0)
.LBB0_642:
	s_andn2_saveexec_b64 s[6:7], s[8:9]
	s_cbranch_execz .LBB0_662
	s_mov_b64 s[8:9], exec
	buffer_wbl2 sc1
	buffer_inv sc1
	s_waitcnt lgkmcnt(0)
	s_waitcnt vmcnt(0)
	v_mbcnt_lo_u32_b32 v1, s8, 0
	v_mbcnt_hi_u32_b32 v1, s9, v1
	v_cmp_eq_u32_e32 vcc, 0, v1
	s_and_saveexec_b64 s[10:11], vcc
	s_cbranch_execz .LBB0_645
	s_bcnt1_i32_b64 s3, s[8:9]
	v_readlane_b32 s6, v254, 9
	v_mov_b32_e32 v2, s3
	v_readlane_b32 s7, v254, 10
	s_nop 4
	global_atomic_add v2, v195, v2, s[6:7] sc0

.LBB0_659:
	s_or_b64 exec, exec, s[8:9]
	s_mov_b64 s[8:9], exec
	v_mbcnt_lo_u32_b32 v0, s8, 0
	v_mbcnt_hi_u32_b32 v0, s9, v0
	v_cmp_eq_u32_e32 vcc, 0, v0
	s_waitcnt vmcnt(0)
	s_and_saveexec_b64 s[10:11], vcc
	s_cbranch_execz .LBB0_661
	s_bcnt1_i32_b64 s3, s[8:9]
	v_mov_b32_e32 v0, s3
	v_mov_b32_e32 v1, 0x2000
	global_atomic_add v1, v0, s[4:5] offset:1024

.LBB0_730:
	s_or_b64 exec, exec, s[10:11]
	v_cvt_f32_u32_e32 v4, v2
	s_waitcnt vmcnt(0)
	v_readfirstlane_b32 s3, v3
	v_sub_u32_e32 v3, 0, v2
	v_rcp_iflag_f32_e32 v4, v4
	v_add_u32_e32 v5, s3, v1
	v_mul_f32_e32 v4, 0x4f7ffffe, v4
	v_cvt_u32_f32_e32 v4, v4
	v_mul_lo_u32 v1, v3, v4
	v_mul_hi_u32 v1, v4, v1
	v_add_u32_e32 v1, v4, v1
	v_mul_hi_u32 v1, v5, v1
	v_mul_lo_u32 v3, v1, v2
	v_sub_u32_e32 v3, v5, v3
	v_add_u32_e32 v4, 1, v1
	v_cmp_ge_u32_e32 vcc, v3, v2
	s_nop 1
	v_cndmask_b32_e32 v1, v1, v4, vcc
	v_sub_u32_e32 v4, v3, v2
	v_cndmask_b32_e32 v3, v3, v4, vcc
	v_add_u32_e32 v4, 1, v1
	v_cmp_ge_u32_e32 vcc, v3, v2
	v_add_u32_e32 v3, 1, v5
	s_nop 0
	v_cndmask_b32_e32 v1, v1, v4, vcc
	v_mul_lo_u32 v4, v2, v1
	v_add_u32_e32 v2, v4, v2
	v_cmp_ne_u32_e32 vcc, v3, v2
	s_and_saveexec_b64 s[6:7], vcc
	s_xor_b64 s[8:9], exec, s[6:7]
	s_cbranch_execz .LBB0_744
	s_waitcnt lgkmcnt(0)
	v_mov_b32_e32 v0, 0x2000
	global_load_dword v0, v0, s[4:5] offset:1024 sc1
	buffer_inv sc1
	s_add_u32 s14, s4, 0x2400
	s_addc_u32 s15, s5, 0
	s_waitcnt vmcnt(1)
	v_cmp_eq_u32_e32 vcc, v0, v1
	s_and_saveexec_b64 s[10:11], vcc
	s_cbranch_execz .LBB0_743
	s_mov_b32 s3, 1
	s_mov_b64 s[18:19], 0
	s_branch .LBB0_734

.LBB0_1290:
	s_mov_b64 s[6:7], exec
	buffer_wbl2 sc1
	buffer_inv sc1
	s_waitcnt lgkmcnt(0)
	s_waitcnt vmcnt(0)
	v_mbcnt_lo_u32_b32 v1, s6, 0
	v_mbcnt_hi_u32_b32 v1, s7, v1
	v_cmp_eq_u32_e32 vcc, 0, v1
	s_and_saveexec_b64 s[8:9], vcc
	s_cbranch_execz .LBB0_1292
	s_bcnt1_i32_b64 s3, s[6:7]
	v_readlane_b32 s6, v254, 9
	v_mov_b32_e32 v2, s3
	v_readlane_b32 s7, v254, 10
	s_nop 4
	global_atomic_add v2, v195, v2, s[6:7] sc0

.LBB0_1306:
	s_or_b64 exec, exec, s[6:7]
	s_mov_b64 s[6:7], exec
	v_mbcnt_lo_u32_b32 v0, s6, 0
	v_mbcnt_hi_u32_b32 v0, s7, v0
	v_cmp_eq_u32_e32 vcc, 0, v0
	s_waitcnt vmcnt(0)
	s_and_saveexec_b64 s[8:9], vcc
	s_cbranch_execnz .LBB0_1307
	s_getpc_b64 s[98:99]
